# retO tasks of the 24 two-B-task blocks per XCD moved to their one-B-task CU partners (work rebalancing inside phase_mix)
# baseline (speedup 1.0000x reference)
.LBB0_181:
	s_or_b64 exec, exec, s[0:1]
	v_readlane_b32 s0, v242, 8
	v_readlane_b32 s1, v242, 9
	s_and_b64 vcc, exec, s[0:1]
	s_barrier
	s_cbranch_vccnz .LBB0_194
	s_cmp_lt_u32 s95, 24
	s_cbranch_scc1 .LBB0_194
	v_readlane_b32 s0, v242, 14
	v_readlane_b32 s1, v242, 15
	s_and_b64 s[0:1], s[0:1], exec
	s_cselect_b32 s0, 6, 9
	v_readlane_b32 s1, v242, 4
	s_lshl_b32 s0, s1, s0
	v_writelane_b32 v242, s0, 25
	s_nop 0
	v_readlane_b32 s0, v242, 17
	v_readlane_b32 s1, v242, 18
	s_mulk_i32 s0, 0x60
	s_ashr_i32 s1, s0, 31
	s_lshl_b64 s[0:1], s[0:1], 2
	s_branch .LBB0_184
.LBB0_183:
	v_readlane_b32 s95, v242, 24
	v_readlane_b32 s98, v242, 22
	v_readlane_b32 s99, v242, 23
	s_cmp_lt_u32 s95, 32
	s_cbranch_scc1 .LBB0_194
	s_cmp_ge_u32 s95, 56
	s_cbranch_scc1 .LBB0_194
	s_sub_u32 s95, s95, 32
